# gmlp item: v-operand column groups 2..4 loaded together with group 1 into spare registers instead of one waited round trip per group
# baseline (speedup 1.0000x reference)
; __device__ __forceinline__ float bflo(unsigned w) { return __uint_as_float(w << 16); }
; __device__ __forceinline__ float bfhi(unsigned w) { return __uint_as_float(w & 0xffff0000u); }
; __device__ __forceinline__ float gelu_t(float x) { return x * sigm(1.5957691216057308f * (x + 0.044715f * x * x * x)); }
; __device__ __forceinline__ void gmlp_item(const Params& p, int l, int item, LAS unsigned char* lds) {
;     ...
;     const size_t Tw = T0 + wid * 16 + fr;
;     bf16x8 bwp[4]; u32x2 uwp[4];
;     { const bf16_t* wp = p.gmw + (((size_t)l * 4 + g) * 128 + wid * 16 + fr) * 128 + fq * 8;
; #pragma unroll
;       for (int ks = 0; ks < 4; ++ks) bwp[ks] = *(const bf16x8*)(wp + (ks < nks ? ks : 0) * 32);
; #pragma unroll
;       for (int ct = 0; ct < 4; ++ct) uwp[ct] = *(const u32x2*)(p.z + Tw * ZLD + 1792 + g * 64 + ct * 16 + fq * 4); }
;     const float bsv = p.gm_bs[((size_t)l * 4 + g) * 128 + wid * 16 + fr];
;     { const int pp = tid >> 2, qd = tid & 3; const bf16_t* vp = p.z + (T0 + pp) * ZLD + 2048 + qd * 16;
;       float keep[16]; float ss = 0.f;
; #pragma unroll
;       for (int i = 0; i < 16; ++i) keep[i] = 0.f;
; #pragma unroll
;       for (int gg = 0; gg < 4; ++gg) { const u32x4 w0 = *(const u32x4*)(vp + gg * 64), w1 = *(const u32x4*)(vp + gg * 64 + 8);
;           const float v[16] = {bflo(w0.x), bfhi(w0.x), bflo(w0.y), bfhi(w0.y), bflo(w0.z), bfhi(w0.z), bflo(w0.w), bfhi(w0.w),
;                                bflo(w1.x), bfhi(w1.x), bflo(w1.y), bfhi(w1.y), bflo(w1.z), bfhi(w1.z), bflo(w1.w), bfhi(w1.w)};
; #pragma unroll
;           for (int i = 0; i < 16; ++i) { const float ge = gelu_t(v[i]); ss += ge * ge; keep[i] = (gg == g) ? ge : keep[i]; } }
.LBB0_319:
	s_and_b64 vcc, exec, s[6:7]
	s_cbranch_vccz .LBB0_342
	v_mov_b32_e32 v34, v202
	s_bfe_u32 s37, s72, 0x20003
	s_lshl_b32 s96, s37, 7
	v_ashrrev_i32_e32 v30, 2, v34
	v_and_b32_e32 v32, 15, v34
	v_and_b32_e32 v0, -16, v30
	s_or_b32 s6, s26, s96
	v_ashrrev_i32_e32 v1, 31, v0
	v_or_b32_e32 v4, s6, v32
	v_mov_b32_e32 v5, s27
	v_lshl_add_u64 v[22:23], v[4:5], 0, v[0:1]
	v_bfe_u32 v48, v34, 4, 2
	v_ashrrev_i32_e32 v33, 7, v34
	v_lshlrev_b64 v[4:5], 8, v[22:23]
	v_lshl_add_u64 v[4:5], s[4:5], 0, v[4:5]
	v_lshlrev_b32_e32 v28, 4, v48
	v_mov_b32_e32 v29, v2
	v_cmp_gt_i32_e32 vcc, 1, v33
	v_lshl_add_u64 v[4:5], v[4:5], 0, v[28:29]
	v_mov_b32_e32 v7, v2
	v_cndmask_b32_e64 v6, 64, 0, vcc
	v_mov_b32_e32 v20, s0
	s_add_i32 s0, s21, 0xffffff00
	s_waitcnt lgkmcnt(0)
	s_barrier
	v_lshl_add_u64 v[6:7], v[4:5], 0, v[6:7]
	v_cmp_gt_i32_e32 vcc, 2, v33
	v_mov_b32_e32 v21, s14
	s_ashr_i32 s14, s0, 6
	global_load_dwordx4 v[16:19], v[4:5], off
	global_load_dwordx4 v[12:15], v[6:7], off
	v_cndmask_b32_e64 v6, v243, 0, vcc
	v_mov_b32_e32 v7, v2
	s_ashr_i32 s15, s14, 31
	s_lshl_b32 s0, s16, 5
	v_lshl_add_u64 v[6:7], v[4:5], 0, v[6:7]
	v_cmp_gt_i32_e64 s[8:9], 3, v33
	s_and_b32 s0, s0, 0x780
	global_load_dwordx4 v[8:11], v[6:7], off
	v_cndmask_b32_e64 v6, v254, 0, s[8:9]
	s_lshl_b64 s[8:9], s[14:15], 11
	s_or_b32 s8, s8, s0
	v_lshl_add_u64 v[46:47], s[8:9], 0, v[0:1]
	v_or_b32_e32 v46, v46, v32
	v_mov_b64_e32 v[26:27], s[34:35]
	s_movk_i32 s0, 0x1600
	v_mad_u64_u32 v[0:1], s[14:15], v46, s0, v[26:27]
	v_mad_i32_i24 v1, v47, s0, v1
	v_lshlrev_b32_e32 v24, 3, v48
	v_mov_b32_e32 v25, v2
	v_mov_b32_e32 v7, v2
	v_lshl_add_u64 v[0:1], v[0:1], 0, s[96:97]
	v_lshl_add_u64 v[4:5], v[4:5], 0, v[6:7]
	v_lshl_add_u64 v[0:1], v[0:1], 0, v[24:25]
	v_lshl_add_u64 v[20:21], v[22:23], 2, v[20:21]
	v_ashrrev_i32_e32 v31, 31, v30
	global_load_dwordx4 v[4:7], v[4:5], off
	s_nop 0
	global_load_dwordx2 v[44:45], v[0:1], off offset:3584
	global_load_dwordx2 v[42:43], v[0:1], off offset:3616
	global_load_dwordx2 v[40:41], v[0:1], off offset:3648
	s_nop 0
	global_load_dwordx2 v[0:1], v[0:1], off offset:3680
	s_cmp_eq_u32 s37, 0
	global_load_dword v3, v[20:21], off
	v_lshl_add_u64 v[20:21], s[8:9], 0, v[30:31]
	v_mad_u64_u32 v[22:23], s[8:9], v20, s0, v[26:27]
	v_lshlrev_b32_e32 v20, 4, v34
	v_and_b32_e32 v29, 48, v20
	v_mad_i32_i24 v23, v21, s0, v23
	v_lshlrev_b32_e32 v20, 1, v29
	v_mov_b32_e32 v21, v2
	v_lshl_add_u64 v[20:21], v[22:23], 0, v[20:21]
	s_mov_b64 s[8:9], 0x1000
	v_lshl_add_u64 v[24:25], v[20:21], 0, s[8:9]
	v_add_co_u32_e64 v20, s[8:9], s80, v20
	v_lshlrev_b32_e32 v30, 1, v30
	s_nop 0
	v_addc_co_u32_e64 v21, s[8:9], 0, v21, s[8:9]
	global_load_dwordx4 v[20:23], v[20:21], off
	s_nop 0
	global_load_dwordx4 v[34:37], v[24:25], off offset:16
	global_load_dwordx4 v[102:105], v[24:25], off offset:144
	global_load_dwordx4 v[106:109], v[24:25], off offset:128
	global_load_dwordx4 v[110:113], v[24:25], off offset:272
	global_load_dwordx4 v[114:117], v[24:25], off offset:256
	global_load_dwordx4 v[118:121], v[24:25], off offset:400
	global_load_dwordx4 v[122:125], v[24:25], off offset:384
	s_cselect_b64 s[8:9], -1, 0
	s_cmp_eq_u32 s37, 1
	v_cmp_lt_i32_e64 s[6:7], 0, v33
	v_cmp_lt_i32_e64 s[4:5], 1, v33
	v_cmp_lt_i32_e32 vcc, 2, v33
	s_waitcnt vmcnt(7)
	v_lshlrev_b32_e32 v26, 16, v20
	v_mul_f32_e32 v31, 0x3d372713, v26
	v_mul_f32_e32 v31, v31, v26
	v_fma_f32 v31, v31, v26, v26
	v_mul_f32_e32 v31, 0x3fcc422a, v31
	v_mul_f32_e32 v31, 0xbfb8aa3b, v31
	v_exp_f32_e32 v31, v31
	v_and_b32_e32 v20, 0xffff0000, v20
	v_lshlrev_b32_e32 v27, 16, v21
	v_and_b32_e32 v21, 0xffff0000, v21
	v_add_f32_e32 v31, 1.0, v31
	v_rcp_f32_e32 v31, v31
	v_lshlrev_b32_e32 v38, 16, v22
	v_and_b32_e32 v22, 0xffff0000, v22
	v_lshlrev_b32_e32 v39, 16, v23
	v_mul_f32_e32 v26, v31, v26
	v_mul_f32_e32 v31, 0x3d372713, v20
	v_mul_f32_e32 v31, v31, v20
	v_fma_f32 v31, v31, v20, v20
	v_mul_f32_e32 v31, 0x3fcc422a, v31
	v_mul_f32_e32 v31, 0xbfb8aa3b, v31
	v_exp_f32_e32 v31, v31
	v_cndmask_b32_e64 v53, 0, v26, s[8:9]
	v_and_b32_e32 v23, 0xffff0000, v23
	s_waitcnt vmcnt(6)
	v_lshlrev_b32_e32 v49, 16, v34
	v_add_f32_e32 v31, 1.0, v31
	v_rcp_f32_e32 v31, v31
	v_and_b32_e32 v34, 0xffff0000, v34
	v_lshlrev_b32_e32 v50, 16, v35
	v_and_b32_e32 v35, 0xffff0000, v35
	v_mul_f32_e32 v20, v31, v20
	v_mul_f32_e32 v31, v20, v20
	v_fmac_f32_e32 v31, v26, v26
	v_cndmask_b32_e64 v26, 0, v20, s[8:9]
	v_mul_f32_e32 v20, 0x3d372713, v27
	v_mul_f32_e32 v20, v20, v27
	v_fma_f32 v20, v20, v27, v27
	v_mul_f32_e32 v20, 0x3fcc422a, v20
	v_mul_f32_e32 v20, 0xbfb8aa3b, v20
	v_exp_f32_e32 v20, v20
	v_lshlrev_b32_e32 v51, 16, v36
	v_and_b32_e32 v36, 0xffff0000, v36
	v_lshlrev_b32_e32 v52, 16, v37
	v_add_f32_e32 v20, 1.0, v20
	v_rcp_f32_e32 v20, v20
	v_and_b32_e32 v37, 0xffff0000, v37
	v_mul_f32_e32 v20, v20, v27
	v_fmac_f32_e32 v31, v20, v20
	v_cndmask_b32_e64 v27, 0, v20, s[8:9]
	v_mul_f32_e32 v20, 0x3d372713, v21
	v_mul_f32_e32 v20, v20, v21
	v_fma_f32 v20, v20, v21, v21
	v_mul_f32_e32 v20, 0x3fcc422a, v20
	v_mul_f32_e32 v20, 0xbfb8aa3b, v20
	v_exp_f32_e32 v20, v20
	s_nop 0
	v_add_f32_e32 v20, 1.0, v20
	v_rcp_f32_e32 v20, v20
	s_nop 0
	v_mul_f32_e32 v20, v20, v21
	v_fmac_f32_e32 v31, v20, v20
	v_cndmask_b32_e64 v54, 0, v20, s[8:9]
	v_mul_f32_e32 v20, 0x3d372713, v38
	v_mul_f32_e32 v20, v20, v38
	v_fma_f32 v20, v20, v38, v38
	v_mul_f32_e32 v20, 0x3fcc422a, v20
	v_mul_f32_e32 v20, 0xbfb8aa3b, v20
	v_exp_f32_e32 v20, v20
	s_nop 0
	v_add_f32_e32 v20, 1.0, v20
	v_rcp_f32_e32 v20, v20
	s_nop 0
	v_mul_f32_e32 v20, v20, v38
	v_fmac_f32_e32 v31, v20, v20
	v_cndmask_b32_e64 v38, 0, v20, s[8:9]
	v_mul_f32_e32 v20, 0x3d372713, v22
	v_mul_f32_e32 v20, v20, v22
; __device__ __forceinline__ float bflo(unsigned w) { return __uint_as_float(w << 16); }
; __device__ __forceinline__ float bfhi(unsigned w) { return __uint_as_float(w & 0xffff0000u); }
; __device__ __forceinline__ float gelu_t(float x) { return x * sigm(1.5957691216057308f * (x + 0.044715f * x * x * x)); }
; __device__ __forceinline__ void gmlp_item(const Params& p, int l, int item, LAS unsigned char* lds) {
;     ...
;       for (int gg = 0; gg < 4; ++gg) { const u32x4 w0 = *(const u32x4*)(vp + gg * 64), w1 = *(const u32x4*)(vp + gg * 64 + 8);
;           const float v[16] = {bflo(w0.x), bfhi(w0.x), bflo(w0.y), bfhi(w0.y), bflo(w0.z), bfhi(w0.z), bflo(w0.w), bfhi(w0.w),
;                                bflo(w1.x), bfhi(w1.x), bflo(w1.y), bfhi(w1.y), bflo(w1.z), bfhi(w1.z), bflo(w1.w), bfhi(w1.w)};
; #pragma unroll
;           for (int i = 0; i < 16; ++i) { const float ge = gelu_t(v[i]); ss += ge * ge; keep[i] = (gg == g) ? ge : keep[i]; } }
	v_fma_f32 v20, v20, v22, v22
	v_mul_f32_e32 v20, 0x3fcc422a, v20
	v_mul_f32_e32 v20, 0xbfb8aa3b, v20
	v_exp_f32_e32 v20, v20
	s_nop 0
	v_add_f32_e32 v20, 1.0, v20
	v_rcp_f32_e32 v20, v20
	s_nop 0
	v_mul_f32_e32 v20, v20, v22
	v_fmac_f32_e32 v31, v20, v20
	v_cndmask_b32_e64 v55, 0, v20, s[8:9]
	v_mul_f32_e32 v20, 0x3d372713, v39
	v_mul_f32_e32 v20, v20, v39
	v_fma_f32 v20, v20, v39, v39
	v_mul_f32_e32 v20, 0x3fcc422a, v20
	v_mul_f32_e32 v20, 0xbfb8aa3b, v20
	v_exp_f32_e32 v20, v20
	s_nop 0
	v_add_f32_e32 v20, 1.0, v20
	v_rcp_f32_e32 v20, v20
	s_nop 0
	v_mul_f32_e32 v20, v20, v39
	v_fmac_f32_e32 v31, v20, v20
	v_cndmask_b32_e64 v39, 0, v20, s[8:9]
	v_mul_f32_e32 v20, 0x3d372713, v23
	v_mul_f32_e32 v20, v20, v23
	v_fma_f32 v20, v20, v23, v23
	v_mul_f32_e32 v20, 0x3fcc422a, v20
	v_mul_f32_e32 v20, 0xbfb8aa3b, v20
	v_exp_f32_e32 v20, v20
	s_nop 0
	v_add_f32_e32 v20, 1.0, v20
	v_rcp_f32_e32 v20, v20
	s_nop 0
	v_mul_f32_e32 v20, v20, v23
	v_fmac_f32_e32 v31, v20, v20
	v_cndmask_b32_e64 v56, 0, v20, s[8:9]
	v_mul_f32_e32 v20, 0x3d372713, v49
	v_mul_f32_e32 v20, v20, v49
	v_fma_f32 v20, v20, v49, v49
	v_mul_f32_e32 v20, 0x3fcc422a, v20
	v_mul_f32_e32 v20, 0xbfb8aa3b, v20
	v_exp_f32_e32 v20, v20
	s_nop 0
	v_add_f32_e32 v20, 1.0, v20
	v_rcp_f32_e32 v20, v20
	s_nop 0
	v_mul_f32_e32 v20, v20, v49
	v_fmac_f32_e32 v31, v20, v20
	v_cndmask_b32_e64 v49, 0, v20, s[8:9]
	v_mul_f32_e32 v20, 0x3d372713, v34
	v_mul_f32_e32 v20, v20, v34
	v_fma_f32 v20, v20, v34, v34
	v_mul_f32_e32 v20, 0x3fcc422a, v20
	v_mul_f32_e32 v20, 0xbfb8aa3b, v20
	v_exp_f32_e32 v20, v20
	s_nop 0
	v_add_f32_e32 v20, 1.0, v20
	v_rcp_f32_e32 v20, v20
	s_nop 0
	v_mul_f32_e32 v20, v20, v34
	v_fmac_f32_e32 v31, v20, v20
	v_cndmask_b32_e64 v57, 0, v20, s[8:9]
	v_mul_f32_e32 v20, 0x3d372713, v50
	v_mul_f32_e32 v20, v20, v50
	v_fma_f32 v20, v20, v50, v50
	v_mul_f32_e32 v20, 0x3fcc422a, v20
	v_mul_f32_e32 v20, 0xbfb8aa3b, v20
	v_exp_f32_e32 v20, v20
	s_nop 0
	v_add_f32_e32 v20, 1.0, v20
	v_rcp_f32_e32 v20, v20
	s_nop 0
	v_mul_f32_e32 v20, v20, v50
	v_fmac_f32_e32 v31, v20, v20
	v_cndmask_b32_e64 v50, 0, v20, s[8:9]
	v_mul_f32_e32 v20, 0x3d372713, v35
	v_mul_f32_e32 v20, v20, v35
	v_fma_f32 v20, v20, v35, v35
	v_mul_f32_e32 v20, 0x3fcc422a, v20
	v_mul_f32_e32 v20, 0xbfb8aa3b, v20
	v_exp_f32_e32 v20, v20
	s_nop 0
	v_add_f32_e32 v20, 1.0, v20
	v_rcp_f32_e32 v20, v20
	s_nop 0
	v_mul_f32_e32 v20, v20, v35
	v_fmac_f32_e32 v31, v20, v20
	v_cndmask_b32_e64 v58, 0, v20, s[8:9]
	v_mul_f32_e32 v20, 0x3d372713, v51
	v_mul_f32_e32 v20, v20, v51
	v_fma_f32 v20, v20, v51, v51
	v_mul_f32_e32 v20, 0x3fcc422a, v20
	v_mul_f32_e32 v20, 0xbfb8aa3b, v20
	v_exp_f32_e32 v20, v20
	s_nop 0
	v_add_f32_e32 v20, 1.0, v20
	v_rcp_f32_e32 v20, v20
	s_nop 0
	v_mul_f32_e32 v20, v20, v51
	v_fmac_f32_e32 v31, v20, v20
	v_cndmask_b32_e64 v51, 0, v20, s[8:9]
	v_mul_f32_e32 v20, 0x3d372713, v36
	v_mul_f32_e32 v20, v20, v36
	v_fma_f32 v20, v20, v36, v36
	v_mul_f32_e32 v20, 0x3fcc422a, v20
	v_mul_f32_e32 v20, 0xbfb8aa3b, v20
	v_exp_f32_e32 v20, v20
	s_nop 0
	v_add_f32_e32 v20, 1.0, v20
	v_rcp_f32_e32 v20, v20
	s_nop 0
	v_mul_f32_e32 v20, v20, v36
	v_fmac_f32_e32 v31, v20, v20
	v_cndmask_b32_e64 v59, 0, v20, s[8:9]
	v_mul_f32_e32 v20, 0x3d372713, v52
	v_mul_f32_e32 v20, v20, v52
	v_fma_f32 v20, v20, v52, v52
	v_mul_f32_e32 v20, 0x3fcc422a, v20
	v_mul_f32_e32 v20, 0xbfb8aa3b, v20
	v_exp_f32_e32 v20, v20
	s_nop 0
	v_add_f32_e32 v20, 1.0, v20
	v_rcp_f32_e32 v20, v20
	s_nop 0
	v_mul_f32_e32 v20, v20, v52
	v_fmac_f32_e32 v31, v20, v20
	v_cndmask_b32_e64 v52, 0, v20, s[8:9]
	v_mul_f32_e32 v20, 0x3d372713, v37
	v_mul_f32_e32 v20, v20, v37
	v_fma_f32 v20, v20, v37, v37
	v_mul_f32_e32 v20, 0x3fcc422a, v20
	v_mul_f32_e32 v20, 0xbfb8aa3b, v20
	v_exp_f32_e32 v20, v20
	s_nop 0
	v_add_f32_e32 v20, 1.0, v20
	v_rcp_f32_e32 v20, v20
	s_nop 0
	v_mul_f32_e32 v20, v20, v37
	v_fmac_f32_e32 v31, v20, v20
	v_cndmask_b32_e64 v60, 0, v20, s[8:9]
	s_waitcnt vmcnt(4)
	v_mov_b32_e32 v20, v102
	v_mov_b32_e32 v21, v103
	v_mov_b32_e32 v22, v104
	v_mov_b32_e32 v23, v105
	v_mov_b32_e32 v34, v106
	v_mov_b32_e32 v35, v107
	v_mov_b32_e32 v36, v108
	v_mov_b32_e32 v37, v109
	s_cselect_b64 s[8:9], -1, 0
	s_cmp_eq_u32 s37, 2
	v_lshlrev_b32_e32 v65, 16, v20
	v_lshlrev_b32_e32 v61, 16, v34
	v_mul_f32_e32 v69, 0x3d372713, v61
	v_mul_f32_e32 v69, v69, v61
	v_fma_f32 v69, v69, v61, v61
	v_mul_f32_e32 v69, 0x3fcc422a, v69
	v_mul_f32_e32 v69, 0xbfb8aa3b, v69
	v_exp_f32_e32 v69, v69
	v_and_b32_e32 v34, 0xffff0000, v34
	v_lshlrev_b32_e32 v62, 16, v35
	v_and_b32_e32 v35, 0xffff0000, v35
	v_add_f32_e32 v69, 1.0, v69
	v_rcp_f32_e32 v69, v69
	v_lshlrev_b32_e32 v63, 16, v36
	v_and_b32_e32 v36, 0xffff0000, v36
	v_lshlrev_b32_e32 v64, 16, v37
	v_mul_f32_e32 v61, v69, v61
	v_fmac_f32_e32 v31, v61, v61
	v_cndmask_b32_e64 v53, v53, v61, s[8:9]
	v_mul_f32_e32 v61, 0x3d372713, v34
	v_mul_f32_e32 v61, v61, v34
	v_fma_f32 v61, v61, v34, v34
	v_mul_f32_e32 v61, 0x3fcc422a, v61
	v_mul_f32_e32 v61, 0xbfb8aa3b, v61
	v_exp_f32_e32 v61, v61
	v_and_b32_e32 v37, 0xffff0000, v37
	v_and_b32_e32 v20, 0xffff0000, v20
	v_lshlrev_b32_e32 v66, 16, v21
	v_add_f32_e32 v61, 1.0, v61
	v_rcp_f32_e32 v61, v61
	v_and_b32_e32 v21, 0xffff0000, v21
	v_lshlrev_b32_e32 v67, 16, v22
	v_and_b32_e32 v22, 0xffff0000, v22
	v_mul_f32_e32 v34, v61, v34
	v_fmac_f32_e32 v31, v34, v34
	v_cndmask_b32_e64 v26, v26, v34, s[8:9]
	v_mul_f32_e32 v34, 0x3d372713, v62
	v_mul_f32_e32 v34, v34, v62
	v_fma_f32 v34, v34, v62, v62
	v_mul_f32_e32 v34, 0x3fcc422a, v34
	v_mul_f32_e32 v34, 0xbfb8aa3b, v34
	v_exp_f32_e32 v34, v34
	v_lshlrev_b32_e32 v68, 16, v23
	v_and_b32_e32 v23, 0xffff0000, v23
	v_add_f32_e32 v34, 1.0, v34
	v_rcp_f32_e32 v34, v34
; __device__ __forceinline__ float bflo(unsigned w) { return __uint_as_float(w << 16); }
; __device__ __forceinline__ float bfhi(unsigned w) { return __uint_as_float(w & 0xffff0000u); }
; __device__ __forceinline__ float gelu_t(float x) { return x * sigm(1.5957691216057308f * (x + 0.044715f * x * x * x)); }
; __device__ __forceinline__ void gmlp_item(const Params& p, int l, int item, LAS unsigned char* lds) {
;     ...
;       for (int gg = 0; gg < 4; ++gg) { const u32x4 w0 = *(const u32x4*)(vp + gg * 64), w1 = *(const u32x4*)(vp + gg * 64 + 8);
;           const float v[16] = {bflo(w0.x), bfhi(w0.x), bflo(w0.y), bfhi(w0.y), bflo(w0.z), bfhi(w0.z), bflo(w0.w), bfhi(w0.w),
;                                bflo(w1.x), bfhi(w1.x), bflo(w1.y), bfhi(w1.y), bflo(w1.z), bfhi(w1.z), bflo(w1.w), bfhi(w1.w)};
; #pragma unroll
;           for (int i = 0; i < 16; ++i) { const float ge = gelu_t(v[i]); ss += ge * ge; keep[i] = (gg == g) ? ge : keep[i]; } }
	s_nop 0
	v_mul_f32_e32 v34, v34, v62
	v_fmac_f32_e32 v31, v34, v34
	v_cndmask_b32_e64 v27, v27, v34, s[8:9]
	v_mul_f32_e32 v34, 0x3d372713, v35
	v_mul_f32_e32 v34, v34, v35
	v_fma_f32 v34, v34, v35, v35
	v_mul_f32_e32 v34, 0x3fcc422a, v34
	v_mul_f32_e32 v34, 0xbfb8aa3b, v34
	v_exp_f32_e32 v34, v34
	s_nop 0
	v_add_f32_e32 v34, 1.0, v34
	v_rcp_f32_e32 v34, v34
	s_nop 0
	v_mul_f32_e32 v34, v34, v35
	v_fmac_f32_e32 v31, v34, v34
	v_cndmask_b32_e64 v54, v54, v34, s[8:9]
	v_mul_f32_e32 v34, 0x3d372713, v63
	v_mul_f32_e32 v34, v34, v63
	v_fma_f32 v34, v34, v63, v63
	v_mul_f32_e32 v34, 0x3fcc422a, v34
	v_mul_f32_e32 v34, 0xbfb8aa3b, v34
	v_exp_f32_e32 v34, v34
	s_nop 0
	v_add_f32_e32 v34, 1.0, v34
	v_rcp_f32_e32 v34, v34
	s_nop 0
	v_mul_f32_e32 v34, v34, v63
	v_fmac_f32_e32 v31, v34, v34
	v_cndmask_b32_e64 v38, v38, v34, s[8:9]
	v_mul_f32_e32 v34, 0x3d372713, v36
	v_mul_f32_e32 v34, v34, v36
	v_fma_f32 v34, v34, v36, v36
	v_mul_f32_e32 v34, 0x3fcc422a, v34
	v_mul_f32_e32 v34, 0xbfb8aa3b, v34
	v_exp_f32_e32 v34, v34
	s_nop 0
	v_add_f32_e32 v34, 1.0, v34
	v_rcp_f32_e32 v34, v34
	s_nop 0
	v_mul_f32_e32 v34, v34, v36
	v_fmac_f32_e32 v31, v34, v34
	v_cndmask_b32_e64 v61, v55, v34, s[8:9]
	v_mul_f32_e32 v34, 0x3d372713, v64
	v_mul_f32_e32 v34, v34, v64
	v_fma_f32 v34, v34, v64, v64
	v_mul_f32_e32 v34, 0x3fcc422a, v34
	v_mul_f32_e32 v34, 0xbfb8aa3b, v34
	v_exp_f32_e32 v34, v34
	s_nop 0
	v_add_f32_e32 v34, 1.0, v34
	v_rcp_f32_e32 v34, v34
	s_nop 0
	v_mul_f32_e32 v34, v34, v64
	v_fmac_f32_e32 v31, v34, v34
	v_cndmask_b32_e64 v39, v39, v34, s[8:9]
	v_mul_f32_e32 v34, 0x3d372713, v37
	v_mul_f32_e32 v34, v34, v37
	v_fma_f32 v34, v34, v37, v37
	v_mul_f32_e32 v34, 0x3fcc422a, v34
	v_mul_f32_e32 v34, 0xbfb8aa3b, v34
	v_exp_f32_e32 v34, v34
	s_nop 0
	v_add_f32_e32 v34, 1.0, v34
	v_rcp_f32_e32 v34, v34
	s_nop 0
	v_mul_f32_e32 v34, v34, v37
	v_fmac_f32_e32 v31, v34, v34
	v_cndmask_b32_e64 v62, v56, v34, s[8:9]
	v_mul_f32_e32 v34, 0x3d372713, v65
	v_mul_f32_e32 v34, v34, v65
	v_fma_f32 v34, v34, v65, v65
	v_mul_f32_e32 v34, 0x3fcc422a, v34
	v_mul_f32_e32 v34, 0xbfb8aa3b, v34
	v_exp_f32_e32 v34, v34
	s_nop 0
	v_add_f32_e32 v34, 1.0, v34
	v_rcp_f32_e32 v34, v34
	s_nop 0
	v_mul_f32_e32 v34, v34, v65
	v_fmac_f32_e32 v31, v34, v34
	v_cndmask_b32_e64 v49, v49, v34, s[8:9]
	v_mul_f32_e32 v34, 0x3d372713, v20
	v_mul_f32_e32 v34, v34, v20
	v_fma_f32 v34, v34, v20, v20
	v_mul_f32_e32 v34, 0x3fcc422a, v34
	v_mul_f32_e32 v34, 0xbfb8aa3b, v34
	v_exp_f32_e32 v34, v34
	s_nop 0
	v_add_f32_e32 v34, 1.0, v34
	v_rcp_f32_e32 v34, v34
	s_nop 0
	v_mul_f32_e32 v20, v34, v20
	v_fmac_f32_e32 v31, v20, v20
	v_cndmask_b32_e64 v63, v57, v20, s[8:9]
	v_mul_f32_e32 v20, 0x3d372713, v66
	v_mul_f32_e32 v20, v20, v66
	v_fma_f32 v20, v20, v66, v66
	v_mul_f32_e32 v20, 0x3fcc422a, v20
	v_mul_f32_e32 v20, 0xbfb8aa3b, v20
	v_exp_f32_e32 v20, v20
	s_nop 0
	v_add_f32_e32 v20, 1.0, v20
	v_rcp_f32_e32 v20, v20
	s_nop 0
	v_mul_f32_e32 v20, v20, v66
	v_fmac_f32_e32 v31, v20, v20
	v_cndmask_b32_e64 v64, v50, v20, s[8:9]
	v_mul_f32_e32 v20, 0x3d372713, v21
	v_mul_f32_e32 v20, v20, v21
	v_fma_f32 v20, v20, v21, v21
	v_mul_f32_e32 v20, 0x3fcc422a, v20
	v_mul_f32_e32 v20, 0xbfb8aa3b, v20
	v_exp_f32_e32 v20, v20
	s_nop 0
	v_add_f32_e32 v20, 1.0, v20
	v_rcp_f32_e32 v20, v20
	s_nop 0
	v_mul_f32_e32 v20, v20, v21
	v_fmac_f32_e32 v31, v20, v20
	v_cndmask_b32_e64 v65, v58, v20, s[8:9]
	v_mul_f32_e32 v20, 0x3d372713, v67
	v_mul_f32_e32 v20, v20, v67
	v_fma_f32 v20, v20, v67, v67
	v_mul_f32_e32 v20, 0x3fcc422a, v20
	v_mul_f32_e32 v20, 0xbfb8aa3b, v20
	v_exp_f32_e32 v20, v20
	s_nop 0
	v_add_f32_e32 v20, 1.0, v20
	v_rcp_f32_e32 v20, v20
	s_nop 0
	v_mul_f32_e32 v20, v20, v67
	v_fmac_f32_e32 v31, v20, v20
	v_cndmask_b32_e64 v66, v51, v20, s[8:9]
	v_mul_f32_e32 v20, 0x3d372713, v22
	v_mul_f32_e32 v20, v20, v22
	v_fma_f32 v20, v20, v22, v22
	v_mul_f32_e32 v20, 0x3fcc422a, v20
	v_mul_f32_e32 v20, 0xbfb8aa3b, v20
	v_exp_f32_e32 v20, v20
	s_nop 0
	v_add_f32_e32 v20, 1.0, v20
	v_rcp_f32_e32 v20, v20
	s_nop 0
	v_mul_f32_e32 v20, v20, v22
	v_fmac_f32_e32 v31, v20, v20
	v_cndmask_b32_e64 v59, v59, v20, s[8:9]
	v_mul_f32_e32 v20, 0x3d372713, v68
	v_mul_f32_e32 v20, v20, v68
	v_fma_f32 v20, v20, v68, v68
	v_mul_f32_e32 v20, 0x3fcc422a, v20
	v_mul_f32_e32 v20, 0xbfb8aa3b, v20
	v_exp_f32_e32 v20, v20
	s_nop 0
	v_add_f32_e32 v20, 1.0, v20
	v_rcp_f32_e32 v20, v20
	s_nop 0
	v_mul_f32_e32 v20, v20, v68
	v_fmac_f32_e32 v31, v20, v20
	v_cndmask_b32_e64 v67, v52, v20, s[8:9]
	v_mul_f32_e32 v20, 0x3d372713, v23
	v_mul_f32_e32 v20, v20, v23
	v_fma_f32 v20, v20, v23, v23
	v_mul_f32_e32 v20, 0x3fcc422a, v20
	v_mul_f32_e32 v20, 0xbfb8aa3b, v20
	v_exp_f32_e32 v20, v20
	s_nop 0
	v_add_f32_e32 v20, 1.0, v20
	v_rcp_f32_e32 v20, v20
	s_nop 0
	v_mul_f32_e32 v20, v20, v23
	v_fmac_f32_e32 v31, v20, v20
	v_cndmask_b32_e64 v60, v60, v20, s[8:9]
	s_waitcnt vmcnt(2)
; __device__ __forceinline__ float bflo(unsigned w) { return __uint_as_float(w << 16); }
; __device__ __forceinline__ float bfhi(unsigned w) { return __uint_as_float(w & 0xffff0000u); }
; __device__ __forceinline__ float gelu_t(float x) { return x * sigm(1.5957691216057308f * (x + 0.044715f * x * x * x)); }
; __device__ __forceinline__ void gmlp_item(const Params& p, int l, int item, LAS unsigned char* lds) {
;     ...
;       for (int gg = 0; gg < 4; ++gg) { const u32x4 w0 = *(const u32x4*)(vp + gg * 64), w1 = *(const u32x4*)(vp + gg * 64 + 8);
;           const float v[16] = {bflo(w0.x), bfhi(w0.x), bflo(w0.y), bfhi(w0.y), bflo(w0.z), bfhi(w0.z), bflo(w0.w), bfhi(w0.w),
;                                bflo(w1.x), bfhi(w1.x), bflo(w1.y), bfhi(w1.y), bflo(w1.z), bfhi(w1.z), bflo(w1.w), bfhi(w1.w)};
; #pragma unroll
;           for (int i = 0; i < 16; ++i) { const float ge = gelu_t(v[i]); ss += ge * ge; keep[i] = (gg == g) ? ge : keep[i]; } }
	v_mov_b32_e32 v20, v110
	v_mov_b32_e32 v21, v111
	v_mov_b32_e32 v22, v112
	v_mov_b32_e32 v23, v113
	v_mov_b32_e32 v34, v114
	v_mov_b32_e32 v35, v115
	v_mov_b32_e32 v36, v116
	v_mov_b32_e32 v37, v117
	s_cselect_b64 s[8:9], -1, 0
	s_cmp_eq_u32 s37, 3
	v_lshlrev_b32_e32 v69, 16, v20
	v_lshlrev_b32_e32 v50, 16, v34
	v_mul_f32_e32 v55, 0x3d372713, v50
	v_mul_f32_e32 v55, v55, v50
	v_fma_f32 v55, v55, v50, v50
	v_mul_f32_e32 v55, 0x3fcc422a, v55
	v_mul_f32_e32 v55, 0xbfb8aa3b, v55
	v_exp_f32_e32 v55, v55
	v_and_b32_e32 v34, 0xffff0000, v34
	v_lshlrev_b32_e32 v51, 16, v35
	v_and_b32_e32 v35, 0xffff0000, v35
	v_add_f32_e32 v55, 1.0, v55
	v_rcp_f32_e32 v55, v55
	v_lshlrev_b32_e32 v52, 16, v36
	v_and_b32_e32 v36, 0xffff0000, v36
	v_lshlrev_b32_e32 v68, 16, v37
	v_mul_f32_e32 v50, v55, v50
	v_fmac_f32_e32 v31, v50, v50
	v_cndmask_b32_e64 v58, v53, v50, s[8:9]
	v_mul_f32_e32 v50, 0x3d372713, v34
	v_mul_f32_e32 v50, v50, v34
	v_fma_f32 v50, v50, v34, v34
	v_mul_f32_e32 v50, 0x3fcc422a, v50
	v_mul_f32_e32 v50, 0xbfb8aa3b, v50
	v_exp_f32_e32 v50, v50
	v_and_b32_e32 v37, 0xffff0000, v37
	v_and_b32_e32 v20, 0xffff0000, v20
	v_lshlrev_b32_e32 v70, 16, v21
	v_add_f32_e32 v50, 1.0, v50
	v_rcp_f32_e32 v50, v50
	v_and_b32_e32 v21, 0xffff0000, v21
	v_lshlrev_b32_e32 v71, 16, v22
	v_and_b32_e32 v22, 0xffff0000, v22
	v_mul_f32_e32 v34, v50, v34
	v_cndmask_b32_e64 v57, v26, v34, s[8:9]
	v_mul_f32_e32 v26, 0x3d372713, v51
	v_mul_f32_e32 v26, v26, v51
	v_fma_f32 v26, v26, v51, v51
	v_mul_f32_e32 v26, 0x3fcc422a, v26
	v_mul_f32_e32 v26, 0xbfb8aa3b, v26
	v_exp_f32_e32 v26, v26
	v_fmac_f32_e32 v31, v34, v34
	v_lshlrev_b32_e32 v72, 16, v23
	v_and_b32_e32 v23, 0xffff0000, v23
	v_add_f32_e32 v26, 1.0, v26
	v_rcp_f32_e32 v26, v26
	s_nop 0
	v_mul_f32_e32 v26, v26, v51
	v_fmac_f32_e32 v31, v26, v26
	v_cndmask_b32_e64 v56, v27, v26, s[8:9]
	v_mul_f32_e32 v26, 0x3d372713, v35
	v_mul_f32_e32 v26, v26, v35
	v_fma_f32 v26, v26, v35, v35
	v_mul_f32_e32 v26, 0x3fcc422a, v26
	v_mul_f32_e32 v26, 0xbfb8aa3b, v26
	v_exp_f32_e32 v26, v26
	s_nop 0
	v_add_f32_e32 v26, 1.0, v26
	v_rcp_f32_e32 v26, v26
	s_nop 0
	v_mul_f32_e32 v26, v26, v35
	v_fmac_f32_e32 v31, v26, v26
	v_cndmask_b32_e64 v55, v54, v26, s[8:9]
	v_mul_f32_e32 v26, 0x3d372713, v52
	v_mul_f32_e32 v26, v26, v52
	v_fma_f32 v26, v26, v52, v52
	v_mul_f32_e32 v26, 0x3fcc422a, v26
	v_mul_f32_e32 v26, 0xbfb8aa3b, v26
	v_exp_f32_e32 v26, v26
	s_nop 0
	v_add_f32_e32 v26, 1.0, v26
	v_rcp_f32_e32 v26, v26
	s_nop 0
	v_mul_f32_e32 v26, v26, v52
	v_fmac_f32_e32 v31, v26, v26
	v_cndmask_b32_e64 v54, v38, v26, s[8:9]
	v_mul_f32_e32 v26, 0x3d372713, v36
	v_mul_f32_e32 v26, v26, v36
	v_fma_f32 v26, v26, v36, v36
	v_mul_f32_e32 v26, 0x3fcc422a, v26
	v_mul_f32_e32 v26, 0xbfb8aa3b, v26
	v_exp_f32_e32 v26, v26
	s_nop 0
	v_add_f32_e32 v26, 1.0, v26
	v_rcp_f32_e32 v26, v26
	s_nop 0
	v_mul_f32_e32 v26, v26, v36
	v_fmac_f32_e32 v31, v26, v26
	v_cndmask_b32_e64 v53, v61, v26, s[8:9]
	v_mul_f32_e32 v26, 0x3d372713, v68
	v_mul_f32_e32 v26, v26, v68
	v_fma_f32 v26, v26, v68, v68
	v_mul_f32_e32 v26, 0x3fcc422a, v26
	v_mul_f32_e32 v26, 0xbfb8aa3b, v26
	v_exp_f32_e32 v26, v26
	s_nop 0
	v_add_f32_e32 v26, 1.0, v26
	v_rcp_f32_e32 v26, v26
	s_nop 0
	v_mul_f32_e32 v26, v26, v68
	v_fmac_f32_e32 v31, v26, v26
	v_cndmask_b32_e64 v52, v39, v26, s[8:9]
	v_mul_f32_e32 v26, 0x3d372713, v37
	v_mul_f32_e32 v26, v26, v37
	v_fma_f32 v26, v26, v37, v37
	v_mul_f32_e32 v26, 0x3fcc422a, v26
	v_mul_f32_e32 v26, 0xbfb8aa3b, v26
	v_exp_f32_e32 v26, v26
	s_nop 0
	v_add_f32_e32 v26, 1.0, v26
	v_rcp_f32_e32 v26, v26
	s_nop 0
	v_mul_f32_e32 v26, v26, v37
	v_fmac_f32_e32 v31, v26, v26
	v_cndmask_b32_e64 v51, v62, v26, s[8:9]
	v_mul_f32_e32 v26, 0x3d372713, v69
	v_mul_f32_e32 v26, v26, v69
	v_fma_f32 v26, v26, v69, v69
	v_mul_f32_e32 v26, 0x3fcc422a, v26
	v_mul_f32_e32 v26, 0xbfb8aa3b, v26
	v_exp_f32_e32 v26, v26
	s_nop 0
	v_add_f32_e32 v26, 1.0, v26
	v_rcp_f32_e32 v26, v26
	s_nop 0
	v_mul_f32_e32 v26, v26, v69
	v_fmac_f32_e32 v31, v26, v26
	v_cndmask_b32_e64 v49, v49, v26, s[8:9]
	v_mul_f32_e32 v26, 0x3d372713, v20
	v_mul_f32_e32 v26, v26, v20
	v_fma_f32 v26, v26, v20, v20
	v_mul_f32_e32 v26, 0x3fcc422a, v26
	v_mul_f32_e32 v26, 0xbfb8aa3b, v26
	v_exp_f32_e32 v26, v26
	s_nop 0
	v_add_f32_e32 v26, 1.0, v26
	v_rcp_f32_e32 v26, v26
	s_nop 0
	v_mul_f32_e32 v20, v26, v20
	v_fmac_f32_e32 v31, v20, v20
	v_cndmask_b32_e64 v50, v63, v20, s[8:9]
	v_mul_f32_e32 v20, 0x3d372713, v70
	v_mul_f32_e32 v20, v20, v70
	v_fma_f32 v20, v20, v70, v70
	v_mul_f32_e32 v20, 0x3fcc422a, v20
	v_mul_f32_e32 v20, 0xbfb8aa3b, v20
	v_exp_f32_e32 v20, v20
	s_nop 0
	v_add_f32_e32 v20, 1.0, v20
	v_rcp_f32_e32 v20, v20
	s_nop 0
	v_mul_f32_e32 v20, v20, v70
	v_fmac_f32_e32 v31, v20, v20
	v_cndmask_b32_e64 v38, v64, v20, s[8:9]
	v_mul_f32_e32 v20, 0x3d372713, v21
	v_mul_f32_e32 v20, v20, v21
	v_fma_f32 v20, v20, v21, v21
	v_mul_f32_e32 v20, 0x3fcc422a, v20
	v_mul_f32_e32 v20, 0xbfb8aa3b, v20
	v_exp_f32_e32 v20, v20
	s_nop 0
	v_add_f32_e32 v20, 1.0, v20
	v_rcp_f32_e32 v20, v20
	s_nop 0
	v_mul_f32_e32 v20, v20, v21
	v_fmac_f32_e32 v31, v20, v20
	v_cndmask_b32_e64 v39, v65, v20, s[8:9]
	v_mul_f32_e32 v20, 0x3d372713, v71
	v_mul_f32_e32 v20, v20, v71
	v_fma_f32 v20, v20, v71, v71
	v_mul_f32_e32 v20, 0x3fcc422a, v20
	v_mul_f32_e32 v20, 0xbfb8aa3b, v20
	v_exp_f32_e32 v20, v20
	s_nop 0
	v_add_f32_e32 v20, 1.0, v20
	v_rcp_f32_e32 v20, v20
	s_nop 0
	v_mul_f32_e32 v20, v20, v71
	v_fmac_f32_e32 v31, v20, v20
	v_cndmask_b32_e64 v35, v66, v20, s[8:9]
	v_mul_f32_e32 v20, 0x3d372713, v22
	v_mul_f32_e32 v20, v20, v22
	v_fma_f32 v20, v20, v22, v22
	v_mul_f32_e32 v20, 0x3fcc422a, v20
	v_mul_f32_e32 v20, 0xbfb8aa3b, v20
	v_exp_f32_e32 v20, v20
	s_nop 0
	v_add_f32_e32 v20, 1.0, v20
	v_rcp_f32_e32 v20, v20
	s_nop 0
	v_mul_f32_e32 v20, v20, v22
	v_fmac_f32_e32 v31, v20, v20
	v_cndmask_b32_e64 v37, v59, v20, s[8:9]
	v_mul_f32_e32 v20, 0x3d372713, v72
	v_mul_f32_e32 v20, v20, v72
	v_fma_f32 v20, v20, v72, v72
	v_mul_f32_e32 v20, 0x3fcc422a, v20
	v_mul_f32_e32 v20, 0xbfb8aa3b, v20
	v_exp_f32_e32 v20, v20
	s_nop 0
	v_add_f32_e32 v20, 1.0, v20
	v_rcp_f32_e32 v20, v20
	s_nop 0
	v_mul_f32_e32 v20, v20, v72
	v_fmac_f32_e32 v31, v20, v20
	v_cndmask_b32_e64 v34, v67, v20, s[8:9]
	v_mul_f32_e32 v20, 0x3d372713, v23
	v_mul_f32_e32 v20, v20, v23
	v_fma_f32 v20, v20, v23, v23
	v_mul_f32_e32 v20, 0x3fcc422a, v20
	v_mul_f32_e32 v20, 0xbfb8aa3b, v20
	v_exp_f32_e32 v20, v20
	s_nop 0
	v_add_f32_e32 v20, 1.0, v20
	v_rcp_f32_e32 v20, v20
	s_nop 0
	v_mul_f32_e32 v20, v20, v23
	v_fmac_f32_e32 v31, v20, v20
	v_cndmask_b32_e64 v36, v60, v20, s[8:9]
	s_waitcnt vmcnt(0)
; __device__ __forceinline__ float bflo(unsigned w) { return __uint_as_float(w << 16); }
; __device__ __forceinline__ float bfhi(unsigned w) { return __uint_as_float(w & 0xffff0000u); }
; __device__ __forceinline__ float gelu_t(float x) { return x * sigm(1.5957691216057308f * (x + 0.044715f * x * x * x)); }
; __device__ __forceinline__ void gmlp_item(const Params& p, int l, int item, LAS unsigned char* lds) {
;     ...
;       for (int gg = 0; gg < 4; ++gg) { const u32x4 w0 = *(const u32x4*)(vp + gg * 64), w1 = *(const u32x4*)(vp + gg * 64 + 8);
;           const float v[16] = {bflo(w0.x), bfhi(w0.x), bflo(w0.y), bfhi(w0.y), bflo(w0.z), bfhi(w0.z), bflo(w0.w), bfhi(w0.w),
;                                bflo(w1.x), bfhi(w1.x), bflo(w1.y), bfhi(w1.y), bflo(w1.z), bfhi(w1.z), bflo(w1.w), bfhi(w1.w)};
; #pragma unroll
;           for (int i = 0; i < 16; ++i) { const float ge = gelu_t(v[i]); ss += ge * ge; keep[i] = (gg == g) ? ge : keep[i]; } }
	v_mov_b32_e32 v20, v118
	v_mov_b32_e32 v21, v119
	v_mov_b32_e32 v22, v120
	v_mov_b32_e32 v23, v121
	s_nop 0
	v_mov_b32_e32 v24, v122
	v_mov_b32_e32 v25, v123
	v_mov_b32_e32 v26, v124
	v_mov_b32_e32 v27, v125
	s_cselect_b64 s[8:9], -1, 0
	s_waitcnt vmcnt(0)
	v_lshlrev_b32_e32 v59, 16, v24
	v_mul_f32_e32 v63, 0x3d372713, v59
	v_mul_f32_e32 v63, v63, v59
	v_fma_f32 v63, v63, v59, v59
	v_mul_f32_e32 v63, 0x3fcc422a, v63
	v_mul_f32_e32 v63, 0xbfb8aa3b, v63
	v_exp_f32_e32 v63, v63
	v_and_b32_e32 v24, 0xffff0000, v24
	v_lshlrev_b32_e32 v60, 16, v25
	v_and_b32_e32 v25, 0xffff0000, v25
	v_add_f32_e32 v63, 1.0, v63
	v_rcp_f32_e32 v63, v63
	v_lshlrev_b32_e32 v61, 16, v26
	v_and_b32_e32 v26, 0xffff0000, v26
	v_lshlrev_b32_e32 v62, 16, v27
	v_mul_f32_e32 v59, v63, v59
	v_fmac_f32_e32 v31, v59, v59
	v_cndmask_b32_e64 v58, v58, v59, s[8:9]
	v_mul_f32_e32 v59, 0x3d372713, v24
	v_mul_f32_e32 v59, v59, v24
	v_fma_f32 v59, v59, v24, v24
	v_mul_f32_e32 v59, 0x3fcc422a, v59
	v_mul_f32_e32 v59, 0xbfb8aa3b, v59
	v_exp_f32_e32 v59, v59
	v_and_b32_e32 v27, 0xffff0000, v27
	v_add_f32_e32 v59, 1.0, v59
	v_rcp_f32_e32 v59, v59
	s_nop 0
	v_mul_f32_e32 v24, v59, v24
	v_fmac_f32_e32 v31, v24, v24
	v_cndmask_b32_e64 v57, v57, v24, s[8:9]
	v_mul_f32_e32 v24, 0x3d372713, v60
	v_mul_f32_e32 v24, v24, v60
	v_fma_f32 v24, v24, v60, v60
	v_mul_f32_e32 v24, 0x3fcc422a, v24
	v_mul_f32_e32 v24, 0xbfb8aa3b, v24
	v_exp_f32_e32 v24, v24
	s_nop 0
	v_add_f32_e32 v24, 1.0, v24
	v_rcp_f32_e32 v24, v24
	s_nop 0
	v_mul_f32_e32 v24, v24, v60
	v_fmac_f32_e32 v31, v24, v24
	v_cndmask_b32_e64 v56, v56, v24, s[8:9]
	v_mul_f32_e32 v24, 0x3d372713, v25
	v_mul_f32_e32 v24, v24, v25
	v_fma_f32 v24, v24, v25, v25
	v_mul_f32_e32 v24, 0x3fcc422a, v24
	v_mul_f32_e32 v24, 0xbfb8aa3b, v24
	v_exp_f32_e32 v24, v24
	s_nop 0
	v_add_f32_e32 v24, 1.0, v24
	v_rcp_f32_e32 v24, v24
	s_nop 0
	v_mul_f32_e32 v24, v24, v25
	v_fmac_f32_e32 v31, v24, v24
	v_cndmask_b32_e64 v55, v55, v24, s[8:9]
	v_mul_f32_e32 v24, 0x3d372713, v61
	v_mul_f32_e32 v24, v24, v61
	v_fma_f32 v24, v24, v61, v61
	v_mul_f32_e32 v24, 0x3fcc422a, v24
	v_mul_f32_e32 v24, 0xbfb8aa3b, v24
	v_exp_f32_e32 v24, v24
	v_lshlrev_b32_e32 v25, 16, v20
	v_add_f32_e32 v24, 1.0, v24
	v_rcp_f32_e32 v24, v24
	s_nop 0
	v_mul_f32_e32 v24, v24, v61
	v_fmac_f32_e32 v31, v24, v24
	v_cndmask_b32_e64 v54, v54, v24, s[8:9]
	v_mul_f32_e32 v24, 0x3d372713, v26
	v_mul_f32_e32 v24, v24, v26
	v_fma_f32 v24, v24, v26, v26
	v_mul_f32_e32 v24, 0x3fcc422a, v24
	v_mul_f32_e32 v24, 0xbfb8aa3b, v24
	v_exp_f32_e32 v24, v24
	s_nop 0
	v_add_f32_e32 v24, 1.0, v24
	v_rcp_f32_e32 v24, v24
	s_nop 0
	v_mul_f32_e32 v24, v24, v26
	v_fmac_f32_e32 v31, v24, v24
	v_cndmask_b32_e64 v53, v53, v24, s[8:9]
	v_mul_f32_e32 v24, 0x3d372713, v62
	v_mul_f32_e32 v24, v24, v62
	v_fma_f32 v24, v24, v62, v62
	v_mul_f32_e32 v24, 0x3fcc422a, v24
	v_mul_f32_e32 v24, 0xbfb8aa3b, v24
	v_exp_f32_e32 v24, v24
	v_mov_b32_e32 v26, v25
	v_add_f32_e32 v24, 1.0, v24
	v_rcp_f32_e32 v24, v24
	s_nop 0
	v_mul_f32_e32 v24, v24, v62
	v_fmac_f32_e32 v31, v24, v24
	v_cndmask_b32_e64 v52, v52, v24, s[8:9]
	v_mul_f32_e32 v24, 0x3d372713, v27
	v_mul_f32_e32 v24, v24, v27
	v_fma_f32 v24, v24, v27, v27
	v_mul_f32_e32 v24, 0x3fcc422a, v24
	v_mul_f32_e32 v24, 0xbfb8aa3b, v24
	v_exp_f32_e32 v24, v24
	s_nop 0
	v_add_f32_e32 v24, 1.0, v24
	v_rcp_f32_e32 v24, v24
	s_nop 0
	v_mul_f32_e32 v24, v24, v27
	v_fmac_f32_e32 v31, v24, v24
	v_cndmask_b32_e64 v51, v51, v24, s[8:9]
	v_and_b32_e32 v24, 0xffff0000, v20
	v_mul_f32_e32 v20, 0x3d372713, v25
	v_mul_f32_e32 v20, v20, v25
	v_fmac_f32_e32 v26, v20, v26
	v_mul_f32_e32 v20, 0x3fcc422a, v26
	v_mul_f32_e32 v20, 0xbfb8aa3b, v20
	v_exp_f32_e32 v20, v20
	v_mov_b32_e32 v26, v24
	v_add_f32_e32 v20, 1.0, v20
	v_rcp_f32_e32 v27, v20
	v_mul_f32_e32 v20, 0x3d372713, v24
	v_mul_f32_e32 v20, v20, v24
	v_fmac_f32_e32 v26, v20, v26
	v_mul_f32_e32 v20, 0x3fcc422a, v26
	v_mul_f32_e32 v20, 0xbfb8aa3b, v20
	v_exp_f32_e32 v20, v20
	s_nop 0
	v_add_f32_e32 v20, 1.0, v20
	v_rcp_f32_e32 v26, v20
	s_nop 0
	v_pk_mul_f32 v[24:25], v[26:27], v[24:25]
	s_nop 0
	v_pk_mul_f32 v[26:27], v[24:25], v[24:25]
	v_cndmask_b32_e64 v49, v49, v25, s[8:9]
	v_add_f32_e32 v20, v27, v31
	v_lshlrev_b32_e32 v25, 16, v21
	v_add_f32_e32 v31, v26, v20
	v_cndmask_b32_e64 v20, v50, v24, s[8:9]
	v_and_b32_e32 v24, 0xffff0000, v21
	v_mul_f32_e32 v21, 0x3d372713, v25
	v_mul_f32_e32 v21, v21, v25
	v_mov_b32_e32 v26, v25
	v_fmac_f32_e32 v26, v21, v26
	v_mul_f32_e32 v21, 0x3fcc422a, v26
	v_mul_f32_e32 v21, 0xbfb8aa3b, v21
	v_exp_f32_e32 v21, v21
	v_mov_b32_e32 v26, v24
	v_add_f32_e32 v21, 1.0, v21
	v_rcp_f32_e32 v27, v21
	v_mul_f32_e32 v21, 0x3d372713, v24
	v_mul_f32_e32 v21, v21, v24
	v_fmac_f32_e32 v26, v21, v26
	v_mul_f32_e32 v21, 0x3fcc422a, v26
	v_mul_f32_e32 v21, 0xbfb8aa3b, v21
	v_exp_f32_e32 v21, v21
	s_nop 0
	v_add_f32_e32 v21, 1.0, v21
	v_rcp_f32_e32 v26, v21
	s_nop 0
	v_pk_mul_f32 v[24:25], v[26:27], v[24:25]
	s_nop 0
	v_pk_mul_f32 v[26:27], v[24:25], v[24:25]
	s_nop 0
	v_add_f32_e32 v21, v27, v31
	v_cndmask_b32_e64 v31, v38, v25, s[8:9]
	v_lshlrev_b32_e32 v25, 16, v22
	v_add_f32_e32 v38, v26, v21
	v_cndmask_b32_e64 v21, v39, v24, s[8:9]
	v_and_b32_e32 v24, 0xffff0000, v22
	v_mul_f32_e32 v22, 0x3d372713, v25
	v_mul_f32_e32 v22, v22, v25
	v_mov_b32_e32 v26, v25
	v_fmac_f32_e32 v26, v22, v26
	v_mul_f32_e32 v22, 0x3fcc422a, v26
	v_mul_f32_e32 v22, 0xbfb8aa3b, v22
	v_exp_f32_e32 v22, v22
	v_mov_b32_e32 v26, v24
	v_add_f32_e32 v22, 1.0, v22
; __device__ __forceinline__ bf16_t f2bf(float f) { return (bf16_t)(pk2(f, 0.f) & 0xffffu); }
; __device__ __forceinline__ float gelu_t(float x) { return x * sigm(1.5957691216057308f * (x + 0.044715f * x * x * x)); }
; __device__ __forceinline__ void lds_barrier() { asm volatile("s_waitcnt lgkmcnt(0)" ::: "memory"); __builtin_amdgcn_s_barrier(); asm volatile("" ::: "memory"); }
; __device__ __forceinline__ void gmlp_item(const Params& p, int l, int item, LAS unsigned char* lds) {
;     ...
;           for (int i = 0; i < 16; ++i) { const float ge = gelu_t(v[i]); ss += ge * ge; keep[i] = (gg == g) ? ge : keep[i]; } }
;       ss += __shfl_xor(ss, 1); ss += __shfl_xor(ss, 2);
;       const float rstd = rsqrtf(ss * (1.f / 256.f) + EPS);
;       const float* ng = p.gm_norm_g + l * 256 + g * 64 + qd * 16;
; #pragma unroll
;       for (int i = 0; i < 16; ++i) vnT[(qd * 16 + i) * 136 + pp] = f2bf(keep[i] * rstd * ng[i]);
;     }
;     lds_barrier();
;     { f32x4 acc[4];
; #pragma unroll
;       for (int ct = 0; ct < 4; ++ct) acc[ct] = ZERO4;
; #pragma unroll
;       for (int ks = 0; ks < 4; ++ks) if (ks < nks) {
	v_rcp_f32_e32 v27, v22
	v_mul_f32_e32 v22, 0x3d372713, v24
	v_mul_f32_e32 v22, v22, v24
	v_fmac_f32_e32 v26, v22, v26
	v_mul_f32_e32 v22, 0x3fcc422a, v26
	v_mul_f32_e32 v22, 0xbfb8aa3b, v22
	v_exp_f32_e32 v22, v22
	s_nop 0
	v_add_f32_e32 v22, 1.0, v22
	v_rcp_f32_e32 v26, v22
	s_nop 0
	v_pk_mul_f32 v[24:25], v[26:27], v[24:25]
	s_nop 0
	v_pk_mul_f32 v[26:27], v[24:25], v[24:25]
	v_cndmask_b32_e64 v22, v35, v25, s[8:9]
	v_add_f32_e32 v27, v27, v38
	v_add_f32_e32 v25, v26, v27
	v_lshlrev_b32_e32 v27, 16, v23
	v_and_b32_e32 v26, 0xffff0000, v23
	v_mul_f32_e32 v23, 0x3d372713, v27
	v_mul_f32_e32 v23, v23, v27
	v_mov_b32_e32 v35, v27
	v_fmac_f32_e32 v35, v23, v35
	v_mul_f32_e32 v23, 0x3fcc422a, v35
	v_mul_f32_e32 v23, 0xbfb8aa3b, v23
	v_exp_f32_e32 v23, v23
	v_mov_b32_e32 v35, v26
	v_cndmask_b32_e64 v24, v37, v24, s[8:9]
	v_add_f32_e32 v23, 1.0, v23
	v_rcp_f32_e32 v39, v23
	v_mul_f32_e32 v23, 0x3d372713, v26
	v_mul_f32_e32 v23, v23, v26
	v_fmac_f32_e32 v35, v23, v35
	v_mul_f32_e32 v23, 0x3fcc422a, v35
	v_mul_f32_e32 v23, 0xbfb8aa3b, v23
	v_exp_f32_e32 v23, v23
	s_nop 0
	v_add_f32_e32 v23, 1.0, v23
	v_rcp_f32_e32 v38, v23
	s_nop 0
	v_pk_mul_f32 v[38:39], v[38:39], v[26:27]
	s_nop 0
	v_cndmask_b32_e64 v26, v34, v39, s[8:9]
	v_and_b32_e32 v34, 64, v207
	v_pk_mul_f32 v[60:61], v[38:39], v[38:39]
	v_xor_b32_e32 v27, 1, v207
	v_add_u32_e32 v34, 64, v34
	v_add_f32_e32 v23, v61, v25
	v_cndmask_b32_e64 v25, v36, v38, s[8:9]
	v_cmp_lt_i32_e64 s[8:9], v27, v34
	v_add_f32_e32 v23, v60, v23
	v_mov_b32_e32 v39, 0
	v_cndmask_b32_e64 v27, v207, v27, s[8:9]
	v_lshlrev_b32_e32 v27, 2, v27
	ds_bpermute_b32 v27, v27, v23
	s_waitcnt lgkmcnt(0)
	v_add_f32_e32 v23, v23, v27
	v_xor_b32_e32 v27, 2, v207
	v_cmp_lt_i32_e64 s[8:9], v27, v34
	s_nop 1
	v_cndmask_b32_e64 v27, v207, v27, s[8:9]
	v_lshlrev_b32_e32 v27, 2, v27
	ds_bpermute_b32 v27, v27, v23
	s_waitcnt lgkmcnt(0)
	v_add_f32_e32 v23, v23, v27
	v_fmamk_f32 v23, v23, 0x3b800000, v204
	v_cmp_gt_f32_e64 s[8:9], s93, v23
	v_mul_f32_e32 v27, 0x4b800000, v23
	s_nop 0
	v_cndmask_b32_e64 v23, v23, v27, s[8:9]
	v_rsq_f32_e32 v23, v23
	s_nop 0
	v_mul_f32_e32 v27, 0x45800000, v23
	v_cndmask_b32_e64 v27, v23, v27, s[8:9]
	s_lshl_b64 s[8:9], s[28:29], 2
	s_add_u32 s0, s23, s8
	s_addc_u32 s9, s36, s9
	s_lshl_b32 s8, s37, 8
	s_add_u32 s8, s0, s8
	s_addc_u32 s9, s9, 0
	v_lshlrev_b32_e32 v23, 2, v29
	global_load_dwordx4 v[34:37], v23, s[8:9]
	v_mul_u32_u24_e32 v29, 0x110, v29
	v_add3_u32 v29, 0, v30, v29
	v_mul_f32_e32 v30, v57, v27
	v_mul_f32_e32 v38, v58, v27
	v_mul_f32_e32 v20, v20, v27
	s_movk_i32 s0, 0x110
	s_waitcnt vmcnt(0)
	v_mul_f32_e32 v30, v35, v30
	v_cvt_pk_bf16_f32 v30, v30, v2
	ds_write_b16 v29, v30 offset:272
	v_mul_f32_e32 v30, v56, v27
	v_mul_f32_e32 v30, v36, v30
	v_mul_f32_e32 v34, v34, v38
	v_cvt_pk_bf16_f32 v30, v30, v2
	v_cvt_pk_bf16_f32 v34, v34, v2
	ds_write_b16 v29, v30 offset:544
	v_mul_f32_e32 v30, v55, v27
	ds_write_b16 v29, v34
	v_mul_f32_e32 v30, v37, v30
	global_load_dwordx4 v[34:37], v23, s[8:9] offset:16
	v_cvt_pk_bf16_f32 v30, v30, v2
	ds_write_b16 v29, v30 offset:816
	v_mul_f32_e32 v30, v54, v27
	v_mov_b32_e32 v38, 0
	s_waitcnt vmcnt(0)
	v_mul_f32_e32 v30, v34, v30
	v_cvt_pk_bf16_f32 v30, v30, v2
	ds_write_b16 v29, v30 offset:1088
	v_mul_f32_e32 v30, v53, v27
	v_mul_f32_e32 v30, v35, v30
	v_cvt_pk_bf16_f32 v30, v30, v2
	ds_write_b16 v29, v30 offset:1360
	v_mul_f32_e32 v30, v52, v27
	v_mul_f32_e32 v30, v36, v30
	v_cvt_pk_bf16_f32 v30, v30, v2
	ds_write_b16 v29, v30 offset:1632
	v_mul_f32_e32 v30, v51, v27
	v_mul_f32_e32 v30, v37, v30
	global_load_dwordx4 v[34:37], v23, s[8:9] offset:32
	v_cvt_pk_bf16_f32 v30, v30, v2
	ds_write_b16 v29, v30 offset:1904
	v_mul_f32_e32 v30, v49, v27
	s_waitcnt vmcnt(0)
	v_mul_f32_e32 v20, v35, v20
	v_cvt_pk_bf16_f32 v20, v20, v2
	ds_write_b16 v29, v20 offset:2448
	v_mul_f32_e32 v20, v31, v27
	v_mul_f32_e32 v20, v36, v20
	v_cvt_pk_bf16_f32 v20, v20, v2
	ds_write_b16 v29, v20 offset:2720
	v_mul_f32_e32 v20, v21, v27
	v_mul_f32_e32 v30, v34, v30
	v_mul_f32_e32 v20, v37, v20
	v_cvt_pk_bf16_f32 v30, v30, v2
	v_cvt_pk_bf16_f32 v20, v20, v2
	ds_write_b16 v29, v30 offset:2176
	ds_write_b16 v29, v20 offset:2992
	v_mul_f32_e32 v30, v22, v27
	global_load_dwordx4 v[20:23], v23, s[8:9] offset:48
	v_mov_b32_e32 v36, 0
	v_cmp_lt_i32_e64 s[8:9], -1, v33
	v_mov_b32_e32 v37, 0
	v_mov_b32_e32 v33, v36
	v_mov_b32_e32 v34, v36
	v_mov_b32_e32 v35, v36
	v_mov_b32_e32 v31, v36
	s_waitcnt vmcnt(0)
	v_mul_f32_e32 v20, v20, v30
	v_cvt_pk_bf16_f32 v20, v20, v2
	ds_write_b16 v29, v20 offset:3264
	v_mul_f32_e32 v20, v24, v27
	v_mul_f32_e32 v20, v21, v20
	v_cvt_pk_bf16_f32 v20, v20, v2
	ds_write_b16 v29, v20 offset:3536
	v_mul_f32_e32 v20, v26, v27
	v_mul_f32_e32 v20, v22, v20
	v_cvt_pk_bf16_f32 v20, v20, v2
	ds_write_b16 v29, v20 offset:3808
	v_mul_f32_e32 v20, v25, v27
	v_mul_f32_e32 v20, v23, v20
	v_cvt_pk_bf16_f32 v20, v20, v2
	ds_write_b16 v29, v20 offset:4080
	s_waitcnt lgkmcnt(0)
	s_barrier
	v_add_u32_e32 v20, 0, v28
	v_mad_u32_u24 v49, v32, s0, v20
	v_mov_b32_e32 v32, 0
	v_mov_b32_e32 v28, v36
	v_mov_b32_e32 v29, v36
	v_mov_b32_e32 v30, v36
	v_mov_b32_e32 v24, v36
	v_mov_b32_e32 v25, v36
	v_mov_b32_e32 v26, v36
	v_mov_b32_e32 v27, v36
	v_mov_b32_e32 v20, v36
	v_mov_b32_e32 v21, v36
	v_mov_b32_e32 v22, v36
	v_mov_b32_e32 v23, v36
	s_and_saveexec_b64 s[14:15], s[8:9]
	s_cbranch_execnz .LBB0_344
	s_or_b64 exec, exec, s[14:15]
	s_and_saveexec_b64 s[8:9], s[6:7]
	s_cbranch_execnz .LBB0_345
